# baseline (speedup 1.0000x reference)
; template <bool MLA>
; __device__ __forceinline__ void attn_item(unsigned char* smem, const Params& p, int b, int hh, int qt) {
;     constexpr int DQK = MLA ? 192 : 64, NS = DQK / 16, CPR = DQK / 8, KROWB = CPR * 16;
;     constexpr int KBYTES = 64 * KROWB, VBYTES = 128 * 128, STGB = KBYTES + VBYTES;
;     constexpr int NKI = KBYTES / 8192;
;     unsigned char* S0 = smem;
;     const int tid = otid(), lane = tid & 63, w = tid >> 6, l31 = lane & 31, h5 = lane >> 5;
;     const int qpos = NMETA + qt * 256 + w * 32 + l31;
;     const size_t qrow = (size_t)b * L + qpos;
;     const bf16_t* qbase;
;     bf16_t* obase;
;     const bf16_t* k1; const bf16_t* k2 = nullptr; const bf16_t* vt;
;     if constexpr (MLA) {
;         bf16_t* qb = (bf16_t*)(p.ws + OFF_Q);
;         qbase = qb + qrow * 3072 + hh * 192;
;         obase = qb + qrow * 3072 + hh * 192;
;         k1 = (const bf16_t*)(p.ws + OFF_KNOPE) + (size_t)b * L * 2048 + hh * 128;
;         k2 = (const bf16_t*)(p.ws + OFF_KROPE) + (size_t)b * L * 64;
;         vt = (const bf16_t*)(p.ws + OFF_VT) + (size_t)(b * 16 + hh) * 128 * LP;
;     } else {
;         const bf16_t* qk = (const bf16_t*)(p.ws + OFF_DQK);
;         qbase = qk + qrow * 2048 + (hh >> 1) * 128 + (hh & 1) * 64;
;         obase = (bf16_t*)(p.ws + OFF_DOM) + qrow * 2048 + hh * 128;
;         k1 = qk + (size_t)b * L * 2048 + 1024 + (hh >> 1) * 128 + (hh & 1) * 64;
;         vt = (const bf16_t*)(p.ws + OFF_DVT) + (size_t)(b * 8 + (hh >> 1)) * 128 * LP;
;     }
;     bf16x8 qf[NS];
;     attn_load_q<MLA>(p, qbase, qpos, h5, qf);
;     const float c1 = (MLA ? 0.07216878364870322f : 0.125f) * LOG2E;
;     float slope2 = 0.f;
;     if constexpr (!MLA) slope2 = exp2f(-(float)((hh >> 1) + 1)) * LOG2E;
;     const bf16_t* ksrc[NKI]; int kstr[NKI];
;     const bf16_t* vsrc[2];
; #pragma unroll
;     for (int i = 0; i < NKI; ++i) {
;         const int slot = (w + 8 * i) * 64 + lane, row = slot / CPR, pc = slot - row * CPR;
;         const int cl = (pc & ~7) | ((pc & 7) ^ ((row >> 1) & 7));
;         if constexpr (MLA) {
;             if (cl < 16) { ksrc[i] = k1 + (size_t)row * 2048 + cl * 8; kstr[i] = 64 * 2048; }
;             else { ksrc[i] = k2 + (size_t)row * 64 + (cl - 16) * 8; kstr[i] = 64 * 64; }
;         } else { ksrc[i] = k1 + (size_t)row * 2048 + cl * 8; kstr[i] = 64 * 2048; }
;     }
.LBB0_852:
	s_and_b64 vcc, exec, s[0:1]
	s_cbranch_vccz .LBB0_831
	s_ashr_i32 s0, s12, 31
	s_lshr_b32 s1, s0, 28
	s_add_i32 s1, s12, s1
	s_lshr_b32 s0, s0, 24
	s_ashr_i32 s1, s1, 4
	s_add_i32 s0, s12, s0
	s_ashr_i32 s8, s0, 8
	s_lshr_b32 s0, s1, 28
	s_add_i32 s0, s1, s0
	s_and_b32 s0, s0, -16
	s_sub_i32 s9, s1, s0
	v_mov_b32_e32 v50, v166
	s_lshl_b32 s0, s1, 12
	s_lshl_b32 s1, s12, 8
	s_sub_i32 s0, s1, s0
	v_ashrrev_i32_e32 v51, 6, v50
	v_and_b32_e32 v195, 31, v50
	v_lshlrev_b32_e32 v0, 5, v51
	v_or_b32_e32 v2, s0, v195
	v_add3_u32 v10, v2, v0, 16
	v_ashrrev_i32_e32 v11, 31, v10
	v_mad_i64_i32 v[2:3], s[0:1], s8, v180, v[10:11]
	v_mov_b64_e32 v[4:5], s[24:25]
	s_movk_i32 s2, 0x1800
	v_mad_u64_u32 v[4:5], s[0:1], v2, s2, v[4:5]
	s_mul_i32 s0, s9, 0xc0
	v_bfe_u32 v147, v50, 5, 1
	v_mad_i32_i24 v5, v3, s2, v5
	s_ashr_i32 s1, s0, 31
	v_lshlrev_b32_e32 v10, 5, v10
	v_lshl_add_u64 v[150:151], s[0:1], 1, v[4:5]
	v_lshlrev_b32_e32 v0, 4, v147
	v_ashrrev_i32_e32 v11, 31, v10
	v_readlane_b32 s0, v252, 57
	v_lshl_add_u64 v[6:7], v[150:151], 0, v[0:1]
	v_lshlrev_b64 v[10:11], 2, v[10:11]
	v_readlane_b32 s1, v252, 58
	global_load_dwordx4 v[110:113], v[6:7], off
	global_load_dwordx4 v[106:109], v[6:7], off offset:32
	global_load_dwordx4 v[102:105], v[6:7], off offset:64
	global_load_dwordx4 v[98:101], v[6:7], off offset:96
	global_load_dwordx4 v[94:97], v[6:7], off offset:128
	global_load_dwordx4 v[90:93], v[6:7], off offset:160
	global_load_dwordx4 v[86:89], v[6:7], off offset:192
	global_load_dwordx4 v[82:85], v[6:7], off offset:224
	global_load_dwordx4 v[30:33], v[6:7], off offset:256
	global_load_dwordx4 v[2:5], v[6:7], off offset:288
	global_load_dwordx4 v[26:29], v[6:7], off offset:320
	s_nop 0
	global_load_dwordx4 v[6:9], v[6:7], off offset:352
	v_lshl_add_u64 v[12:13], s[0:1], 0, v[10:11]
	v_readlane_b32 s0, v252, 55
	v_readlane_b32 s1, v252, 56
	v_and_b32_e32 v0, 32, v50
	v_lshl_add_u64 v[14:15], v[12:13], 0, v[0:1]
	v_lshl_add_u64 v[10:11], s[0:1], 0, v[10:11]
	v_lshl_add_u64 v[22:23], v[10:11], 0, v[0:1]
	global_load_dwordx4 v[34:37], v[14:15], off offset:16
	global_load_dwordx4 v[42:45], v[14:15], off
	global_load_dwordx4 v[38:41], v[22:23], off offset:16
	global_load_dwordx4 v[46:49], v[22:23], off
	global_load_dwordx4 v[10:13], v[14:15], off offset:80
	global_load_dwordx4 v[18:21], v[14:15], off offset:64
	s_nop 0
	global_load_dwordx4 v[14:17], v[22:23], off offset:80
	s_nop 0
	global_load_dwordx4 v[22:25], v[22:23], off offset:64
	s_mul_i32 s1, s8, 0x1010000
	s_mul_hi_i32 s0, s8, 0x1010000
	s_add_u32 s2, s86, s1
	s_addc_u32 s3, s87, s0
	s_lshl_b32 s0, s9, 7
	s_ashr_i32 s1, s0, 31
	s_lshl_b64 s[0:1], s[0:1], 1
	s_add_u32 s0, s2, s0
	s_addc_u32 s1, s3, s1
	s_mul_i32 s2, s8, 0x80800
	v_readlane_b32 s6, v253, 13
	s_add_u32 s2, s6, s2
	s_mov_b32 s6, 0x2aaaaaab
	v_mul_hi_i32 v0, v50, s6
	v_lshrrev_b32_e32 v52, 31, v0
	v_ashrrev_i32_e32 v0, 2, v0
	v_add_u32_e32 v56, v0, v52
	s_mul_hi_i32 s3, s8, 0x80800
	v_readlane_b32 s7, v253, 14
	s_movk_i32 s6, 0xffe8
	v_lshrrev_b32_e32 v0, 1, v56
	s_addc_u32 s3, s7, s3
	v_mad_u64_u32 v[52:53], s[6:7], v56, s6, v[50:51]
	v_xor_b32_e32 v0, v0, v50
	v_bfi_b32 v0, -8, v52, v0
	v_cmp_lt_i32_e32 vcc, 15, v0
	v_ashrrev_i32_e32 v57, 31, v56
	v_lshlrev_b32_e32 v58, 3, v0
	s_and_saveexec_b64 s[6:7], vcc
	s_xor_b64 s[6:7], exec, s[6:7]
	v_lshlrev_b64 v[52:53], 7, v[56:57]
	v_lshl_add_u64 v[52:53], s[2:3], 0, v[52:53]
	v_add_u32_e32 v0, 0xffffff80, v58
	v_lshl_add_u64 v[52:53], v[0:1], 1, v[52:53]
	s_or_saveexec_b64 s[6:7], s[6:7]
	v_mov_b64_e32 v[54:55], 0x1000
	s_xor_b64 exec, exec, s[6:7]
	v_lshlrev_b64 v[52:53], 12, v[56:57]
	v_lshl_add_u64 v[52:53], s[0:1], 0, v[52:53]
	v_ashrrev_i32_e32 v59, 31, v58
	v_lshl_add_u64 v[52:53], v[58:59], 1, v[52:53]
	v_mov_b64_e32 v[54:55], 0x20000
	s_or_b64 exec, exec, s[6:7]
	v_add_u32_e32 v62, 0x200, v50
	s_mov_b32 s6, 0x2aaaaaab
	v_mul_hi_i32 v0, v62, s6
	v_lshrrev_b32_e32 v55, 31, v0
	v_ashrrev_i32_e32 v0, 2, v0
	v_add_u32_e32 v60, v0, v55
	s_movk_i32 s6, 0xffe8
	v_lshrrev_b32_e32 v0, 1, v60
	v_mad_u64_u32 v[56:57], s[6:7], v60, s6, v[62:63]
	v_xor_b32_e32 v0, v0, v50
	v_bfi_b32 v0, -8, v56, v0
	v_cmp_lt_i32_e32 vcc, 15, v0
	v_ashrrev_i32_e32 v61, 31, v60
	v_lshlrev_b32_e32 v64, 3, v0
	s_and_saveexec_b64 s[6:7], vcc
	s_xor_b64 s[6:7], exec, s[6:7]
	v_lshlrev_b64 v[56:57], 7, v[60:61]
	v_lshl_add_u64 v[56:57], s[2:3], 0, v[56:57]
	v_add_u32_e32 v0, 0xffffff80, v64
	v_lshl_add_u64 v[56:57], v[0:1], 1, v[56:57]
	s_or_saveexec_b64 s[6:7], s[6:7]
	v_mov_b64_e32 v[58:59], 0x1000
	s_xor_b64 exec, exec, s[6:7]
	v_lshlrev_b64 v[56:57], 12, v[60:61]
	v_lshl_add_u64 v[56:57], s[0:1], 0, v[56:57]
	v_ashrrev_i32_e32 v65, 31, v64
	v_lshl_add_u64 v[56:57], v[64:65], 1, v[56:57]
	v_mov_b64_e32 v[58:59], 0x20000
	s_or_b64 exec, exec, s[6:7]
	v_add_u32_e32 v0, 0x400, v50
	s_mov_b32 s6, 0x2aaaaaab
	v_mul_hi_i32 v55, v0, s6
	v_lshrrev_b32_e32 v59, 31, v55
	v_ashrrev_i32_e32 v55, 2, v55
	v_add_u32_e32 v66, v55, v59
	s_movk_i32 s6, 0xffe8
	v_mad_u64_u32 v[60:61], s[6:7], v66, s6, v[0:1]
	v_lshrrev_b32_e32 v0, 1, v66
	v_xor_b32_e32 v0, v0, v50
	v_bfi_b32 v0, -8, v60, v0
	v_cmp_lt_i32_e32 vcc, 15, v0
	v_ashrrev_i32_e32 v67, 31, v66
	v_lshlrev_b32_e32 v68, 3, v0
	s_and_saveexec_b64 s[6:7], vcc
	s_xor_b64 s[6:7], exec, s[6:7]
	v_lshlrev_b64 v[60:61], 7, v[66:67]
	v_lshl_add_u64 v[60:61], s[2:3], 0, v[60:61]
	v_add_u32_e32 v0, 0xffffff80, v68
	v_lshl_add_u64 v[60:61], v[0:1], 1, v[60:61]
	s_or_saveexec_b64 s[2:3], s[6:7]
	v_mov_b64_e32 v[64:65], 0x1000
	s_xor_b64 exec, exec, s[2:3]
	v_lshlrev_b64 v[60:61], 12, v[66:67]
	v_lshl_add_u64 v[60:61], s[0:1], 0, v[60:61]
	v_ashrrev_i32_e32 v69, 31, v68
	v_lshl_add_u64 v[60:61], v[68:69], 1, v[60:61]
	v_mov_b64_e32 v[64:65], 0x20000
	s_or_b64 exec, exec, s[2:3]
	s_waitcnt vmcnt(11)
; __device__ __forceinline__ float bf2f(bf16_t h) { return __uint_as_float(((unsigned)h) << 16); }
; __device__ __forceinline__ bf16_t f2bf(float f) { return (bf16_t)(pack2(f, 0.0f) & 0xFFFFu); }
; #define ATTN_DMA(STAGE) do { unsigned char* sb_ = S0 + (STAGE) * STGB + lane * 16; \
;     _Pragma("unroll") for (int i_ = 0; i_ < NKI; ++i_) { dma16(ksrc[i_], sb_ + (w + 8 * i_) * 1024); ksrc[i_] += kstr[i_]; } \
;     _Pragma("unroll") for (int i_ = 0; i_ < 2; ++i_) { dma16(vsrc[i_], sb_ + KBYTES + (w + 8 * i_) * 1024); vsrc[i_] += 64; } } while (0)
; template <bool MLA>
; __device__ __forceinline__ void attn_load_q(const Params& p, const bf16_t* qbase, int qpos, int h5, bf16x8 (&qf)[MLA ? 12 : 4]) {
;     ...
;         for (int sp = 0; sp < 2; ++sp)
; #pragma unroll
;             for (int j = 0; j < 8; ++j) {
;                 int fi = sp * 16 + h5 * 8 + j;
;                 float x1 = bf2f((bf16_t)qf[8 + sp][j]), x2 = bf2f((bf16_t)qf[10 + sp][j]);
;                 float cs = ct[fi], sn = st[fi];
;                 qf[8 + sp][j] = (short)f2bf(x1 * cs - x2 * sn);
;                 qf[10 + sp][j] = (short)f2bf(x2 * cs + x1 * sn);
;             }
; template <bool MLA>
; __device__ __forceinline__ void attn_item(unsigned char* smem, const Params& p, int b, int hh, int qt) {
;     ...
; #pragma unroll
;     for (int i = 0; i < 2; ++i) {
;         const int slot = (w + 8 * i) * 64 + lane, d = slot >> 3, pc = slot & 7;
;         vsrc[i] = vt + (size_t)d * LP + (pc ^ ((d >> 1) & 7)) * 8;
;     }
;     ...
;     const int yz = h5 ^ ((l31 >> 1) & 7);
;     int off4[4];
; #pragma unroll
;     for (int c = 0; c < 4; ++c) off4[c] = (((2 * c) ^ yz) & 7) * 16;
;     f32x16 o[4];
; #pragma unroll
;     for (int d = 0; d < 4; ++d)
; #pragma unroll
;         for (int r = 0; r < 16; ++r) o[d][r] = 0.f;
;     float m_run = -INFINITY, lsum = 0.f;
;     const int q0w = NMETA + qt * 256 + w * 32;
;     __syncthreads();
;     ATTN_DMA(0);
;     ATTN_DMA(1);
;     if constexpr (MLA) asm volatile("s_waitcnt vmcnt(5)" ::: "memory"); else asm volatile("s_waitcnt vmcnt(3)" ::: "memory");
;     __builtin_amdgcn_s_barrier();
	v_and_b32_e32 v67, 0xffff0000, v30
	v_lshlrev_b32_e32 v66, 16, v30
	s_waitcnt vmcnt(9)
	v_and_b32_e32 v69, 0xffff0000, v26
	v_lshlrev_b32_e32 v68, 16, v26
	s_waitcnt vmcnt(4)
	v_pk_mul_f32 v[70:71], v[46:47], v[66:67]
	v_pk_mul_f32 v[46:47], v[46:47], v[68:69]
	v_pk_fma_f32 v[70:71], v[42:43], v[68:69], v[70:71]
	v_pk_fma_f32 v[42:43], v[42:43], v[66:67], v[46:47] neg_lo:[0,0,1] neg_hi:[0,0,1]
	v_lshlrev_b32_e32 v30, 16, v27
	v_cvt_pk_bf16_f32 v118, v42, v43
	v_and_b32_e32 v43, 0xffff0000, v31
	v_lshlrev_b32_e32 v42, 16, v31
	v_and_b32_e32 v31, 0xffff0000, v27
	v_pk_mul_f32 v[26:27], v[48:49], v[42:43]
	s_lshl_b32 s0, s8, 4
	v_pk_fma_f32 v[26:27], v[44:45], v[30:31], v[26:27]
	s_add_i32 s0, s0, s9
	v_cvt_pk_bf16_f32 v115, v26, v27
	v_pk_mul_f32 v[26:27], v[48:49], v[30:31]
	v_and_b32_e32 v31, 0xffff0000, v28
	v_pk_fma_f32 v[26:27], v[44:45], v[42:43], v[26:27] neg_lo:[0,0,1] neg_hi:[0,0,1]
	v_lshlrev_b32_e32 v30, 16, v28
	v_cvt_pk_bf16_f32 v119, v26, v27
	v_and_b32_e32 v27, 0xffff0000, v32
	v_lshlrev_b32_e32 v26, 16, v32
	v_pk_mul_f32 v[42:43], v[38:39], v[26:27]
	s_mul_i32 s2, s0, 0x104000
	v_pk_fma_f32 v[42:43], v[34:35], v[30:31], v[42:43]
	v_pk_mul_f32 v[30:31], v[38:39], v[30:31]
	s_mul_hi_i32 s1, s0, 0x104000
	v_pk_fma_f32 v[26:27], v[34:35], v[26:27], v[30:31] neg_lo:[0,0,1] neg_hi:[0,0,1]
	v_and_b32_e32 v31, 0xffff0000, v29
	v_cvt_pk_bf16_f32 v120, v26, v27
	v_and_b32_e32 v27, 0xffff0000, v33
	v_lshlrev_b32_e32 v26, 16, v33
	v_lshlrev_b32_e32 v30, 16, v29
	v_pk_mul_f32 v[28:29], v[40:41], v[26:27]
	s_add_u32 s2, s84, s2
	v_pk_fma_f32 v[28:29], v[36:37], v[30:31], v[28:29]
	s_addc_u32 s3, s85, s1
	v_cvt_pk_bf16_f32 v117, v28, v29
	v_pk_mul_f32 v[28:29], v[40:41], v[30:31]
	v_ashrrev_i32_e32 v0, 3, v50
	v_pk_fma_f32 v[26:27], v[36:37], v[26:27], v[28:29] neg_lo:[0,0,1] neg_hi:[0,0,1]
	v_and_b32_e32 v29, 0xffff0000, v6
	v_cvt_pk_bf16_f32 v121, v26, v27
	v_and_b32_e32 v27, 0xffff0000, v2
	v_lshlrev_b32_e32 v26, 16, v2
	v_lshlrev_b32_e32 v28, 16, v6
	s_waitcnt vmcnt(0)
	v_pk_mul_f32 v[30:31], v[22:23], v[26:27]
	v_pk_mul_f32 v[22:23], v[22:23], v[28:29]
	v_pk_fma_f32 v[30:31], v[18:19], v[28:29], v[30:31]
	v_pk_fma_f32 v[18:19], v[18:19], v[26:27], v[22:23] neg_lo:[0,0,1] neg_hi:[0,0,1]
	v_lshlrev_b32_e32 v2, 16, v7
	v_cvt_pk_bf16_f32 v126, v18, v19
	v_and_b32_e32 v19, 0xffff0000, v3
	v_lshlrev_b32_e32 v18, 16, v3
	v_and_b32_e32 v3, 0xffff0000, v7
	v_pk_mul_f32 v[6:7], v[24:25], v[18:19]
	s_movk_i32 s6, 0x2080
	v_pk_fma_f32 v[6:7], v[20:21], v[2:3], v[6:7]
	v_lshrrev_b32_e32 v34, 4, v50
	v_cvt_pk_bf16_f32 v123, v6, v7
	v_mov_b64_e32 v[6:7], s[2:3]
	v_mad_i64_i32 v[22:23], s[2:3], v0, s6, v[6:7]
	v_xor_b32_e32 v0, v34, v50
	v_lshlrev_b32_e32 v0, 4, v0
	v_ashrrev_i32_e32 v35, 3, v62
	v_and_b32_e32 v0, 0x70, v0
	v_mad_i64_i32 v[6:7], s[2:3], v35, s6, v[6:7]
	v_and_b32_e32 v55, 63, v50
	v_lshl_add_u64 v[22:23], v[22:23], 0, v[0:1]
	v_lshl_add_u64 v[6:7], v[6:7], 0, v[0:1]
	v_lshlrev_b32_e32 v0, 10, v51
	v_lshl_or_b32 v199, v55, 4, v0
	v_add_u32_e32 v28, 0x2000, v199
	v_readfirstlane_b32 s1, v199
	v_cvt_pk_bf16_f32 v122, v30, v31
	s_mov_b32 m0, s1
	v_readfirstlane_b32 s1, v28
	v_add_u32_e32 v30, 0x4000, v199
	s_barrier
	global_load_lds_dwordx4 v[52:53], off
	s_mov_b32 m0, s1
	v_readfirstlane_b32 s1, v30
	v_add_u32_e32 v32, 0x6000, v199
	global_load_lds_dwordx4 v[56:57], off
	s_mov_b32 m0, s1
	v_readfirstlane_b32 s1, v32
	v_add_u32_e32 v36, 0x8000, v199
	global_load_lds_dwordx4 v[60:61], off
	s_mov_b32 m0, s1
	v_readfirstlane_b32 s1, v36
	v_add_u32_e32 v36, 0xa000, v199
	v_lshlrev_b32_e32 v0, 1, v54
	global_load_lds_dwordx4 v[22:23], off
	s_mov_b32 m0, s1
	v_readfirstlane_b32 s1, v36
	v_lshl_add_u64 v[26:27], v[52:53], 0, v[0:1]
	global_load_lds_dwordx4 v[6:7], off
	s_mov_b32 m0, s1
	v_lshlrev_b32_e32 v152, 1, v58
	global_load_lds_dwordx4 v[26:27], off
	v_add_u32_e32 v26, 0xc000, v199
	v_mov_b32_e32 v153, v1
	v_readfirstlane_b32 s1, v26
	v_add_u32_e32 v26, 0xe000, v199
	v_lshl_add_u64 v[28:29], v[56:57], 0, v[152:153]
	v_lshlrev_b32_e32 v154, 1, v64
	v_mov_b32_e32 v155, v1
	s_mov_b32 m0, s1
	v_readfirstlane_b32 s1, v26
	v_add_u32_e32 v26, 0x10000, v199
	v_lshl_add_u64 v[30:31], v[60:61], 0, v[154:155]
	global_load_lds_dwordx4 v[28:29], off
	s_mov_b32 m0, s1
	v_readfirstlane_b32 s1, v26
	v_add_u32_e32 v26, 0x12000, v199
	v_lshl_add_u64 v[32:33], v[22:23], 0, s[62:63]
	global_load_lds_dwordx4 v[30:31], off
	s_mov_b32 m0, s1
	v_readfirstlane_b32 s1, v26
	v_lshl_add_u64 v[6:7], v[6:7], 0, s[62:63]
	global_load_lds_dwordx4 v[32:33], off
	s_mov_b32 m0, s1
	v_pk_mul_f32 v[2:3], v[24:25], v[2:3]
	global_load_lds_dwordx4 v[6:7], off
	v_pk_fma_f32 v[2:3], v[20:21], v[18:19], v[2:3] neg_lo:[0,0,1] neg_hi:[0,0,1]
	v_and_b32_e32 v7, 0xffff0000, v8
	v_cvt_pk_bf16_f32 v127, v2, v3
	v_and_b32_e32 v3, 0xffff0000, v4
	v_lshlrev_b32_e32 v2, 16, v4
	v_lshlrev_b32_e32 v6, 16, v8
	v_pk_mul_f32 v[18:19], v[14:15], v[2:3]
	v_lshlrev_b32_e32 v4, 16, v9
	v_pk_fma_f32 v[18:19], v[10:11], v[6:7], v[18:19]
	v_pk_mul_f32 v[6:7], v[14:15], v[6:7]
	s_waitcnt vmcnt(5)
; #define ATTN_DMA(STAGE) do { unsigned char* sb_ = S0 + (STAGE) * STGB + lane * 16; \
;     _Pragma("unroll") for (int i_ = 0; i_ < NKI; ++i_) { dma16(ksrc[i_], sb_ + (w + 8 * i_) * 1024); ksrc[i_] += kstr[i_]; } \
;     _Pragma("unroll") for (int i_ = 0; i_ < 2; ++i_) { dma16(vsrc[i_], sb_ + KBYTES + (w + 8 * i_) * 1024); vsrc[i_] += 64; } } while (0)
; __device__ __forceinline__ void attn_exp(f32x16& sa, float mx, float& m_run, float& lsum, f32x16 (&o)[4], bf16x8& pb0, bf16x8& pb1) {
;     ...
;     float pv[16];
; #pragma unroll
;     for (int r = 0; r < 16; ++r) { pv[r] = __builtin_amdgcn_exp2f(sa[r] - m_run); lsum += pv[r]; }
;     u32x4 t0 = {pack2(pv[0], pv[1]), pack2(pv[2], pv[3]), pack2(pv[4], pv[5]), pack2(pv[6], pv[7])};
;     u32x4 t1 = {pack2(pv[8], pv[9]), pack2(pv[10], pv[11]), pack2(pv[12], pv[13]), pack2(pv[14], pv[15])};
;     pb0 = __builtin_bit_cast(bf16x8, t0);
;     pb1 = __builtin_bit_cast(bf16x8, t1);
; template <bool MLA>
; __device__ __forceinline__ void attn_item(unsigned char* smem, const Params& p, int b, int hh, int qt) {
;     ...
;     f32x16 o[4];
; #pragma unroll
;     for (int d = 0; d < 4; ++d)
; #pragma unroll
;         for (int r = 0; r < 16; ++r) o[d][r] = 0.f;
;     float m_run = -INFINITY, lsum = 0.f;
;     const int q0w = NMETA + qt * 256 + w * 32;
;     __syncthreads();
;     ATTN_DMA(0);
;     ATTN_DMA(1);
;     if constexpr (MLA) asm volatile("s_waitcnt vmcnt(5)" ::: "memory"); else asm volatile("s_waitcnt vmcnt(3)" ::: "memory");
;     __builtin_amdgcn_s_barrier();
;     ...
;     int stage = 0;
	v_cvt_pk_bf16_f32 v116, v42, v43
	v_pk_fma_f32 v[2:3], v[10:11], v[2:3], v[6:7] neg_lo:[0,0,1] neg_hi:[0,0,1]
	v_cvt_pk_bf16_f32 v124, v18, v19
	v_cvt_pk_bf16_f32 v128, v2, v3
	v_and_b32_e32 v3, 0xffff0000, v5
	v_lshlrev_b32_e32 v2, 16, v5
	v_and_b32_e32 v5, 0xffff0000, v9
	v_pk_mul_f32 v[6:7], v[16:17], v[2:3]
	v_mov_b32_e32 v8, v1
	v_pk_fma_f32 v[6:7], v[12:13], v[4:5], v[6:7]
	v_pk_mul_f32 v[4:5], v[16:17], v[4:5]
	v_mov_b32_e32 v16, v1
	v_pk_fma_f32 v[2:3], v[12:13], v[2:3], v[4:5] neg_lo:[0,0,1] neg_hi:[0,0,1]
	v_lshrrev_b32_e32 v4, 1, v50
	v_bitop3_b32 v4, v4, v147, 7 bitop3:0x6c
	v_and_b32_e32 v5, 64, v183
	v_lshlrev_b32_e32 v192, 4, v4
	v_xor_b32_e32 v4, 32, v183
	v_add_u32_e32 v5, 64, v5
	v_cmp_lt_i32_e32 vcc, v4, v5
	v_mov_b32_e32 v5, v1
	v_cvt_pk_bf16_f32 v129, v2, v3
	v_cndmask_b32_e32 v4, v183, v4, vcc
	v_lshlrev_b32_e32 v149, 2, v4
	v_lshlrev_b32_e32 v4, 2, v64
	v_mad_i64_i32 v[2:3], s[2:3], v35, s6, 0
	v_lshl_add_u64 v[158:159], v[60:61], 0, v[4:5]
	v_lshlrev_b32_e32 v4, 2, v58
	v_lshl_add_u64 v[160:161], v[56:57], 0, v[4:5]
	v_lshlrev_b32_e32 v4, 2, v54
	v_mad_i64_i32 v[2:3], s[0:1], s0, v188, v[2:3]
	v_lshl_add_u64 v[162:163], v[52:53], 0, v[4:5]
	v_bitop3_b32 v4, v34, 7, v50 bitop3:0x48
	v_readlane_b32 s0, v251, 7
	s_mov_b64 s[2:3], 0x100
	v_lshl_or_b32 v2, v4, 4, v2
	v_readlane_b32 s1, v251, 8
	v_mov_b32_e32 v17, v1
	v_cvt_pk_bf16_f32 v125, v6, v7
	v_lshl_add_u64 v[156:157], v[22:23], 0, s[2:3]
	v_lshl_add_u64 v[164:165], s[0:1], 0, v[2:3]
	v_mov_b32_e32 v2, v1
	v_mov_b32_e32 v3, v1
	v_mov_b32_e32 v4, v1
	v_mov_b32_e32 v6, v1
	v_mov_b32_e32 v7, v1
	v_mov_b32_e32 v9, v1
	v_mov_b32_e32 v10, v1
	v_mov_b32_e32 v11, v1
	v_mov_b32_e32 v12, v1
	v_mov_b32_e32 v13, v1
	v_mov_b32_e32 v14, v1
	v_mov_b32_e32 v15, v1
	v_mov_b64_e32 v[32:33], v[16:17]
	v_mov_b64_e32 v[48:49], v[16:17]
	v_mov_b64_e32 v[64:65], v[16:17]
	v_cvt_pk_bf16_f32 v114, v70, v71
	v_xor_b32_e32 v193, 32, v192
	v_xor_b32_e32 v196, 64, v192
	v_xor_b32_e32 v197, 0x60, v192
	v_mul_u32_u24_e32 v200, 0x180, v195
	v_lshlrev_b32_e32 v194, 7, v195
	s_mov_b32 s2, 0
	v_mov_b32_e32 v198, 0xff800000
	v_mov_b32_e32 v201, 0
	s_mov_b64 s[0:1], 0
	v_mov_b64_e32 v[30:31], v[14:15]
	v_mov_b64_e32 v[28:29], v[12:13]
	v_mov_b64_e32 v[26:27], v[10:11]
	v_mov_b64_e32 v[24:25], v[8:9]
	v_mov_b64_e32 v[22:23], v[6:7]
	v_mov_b64_e32 v[20:21], v[4:5]
	v_mov_b64_e32 v[18:19], v[2:3]
	v_mov_b64_e32 v[46:47], v[14:15]
	v_mov_b64_e32 v[44:45], v[12:13]
	v_mov_b64_e32 v[42:43], v[10:11]
	v_mov_b64_e32 v[40:41], v[8:9]
	v_mov_b64_e32 v[38:39], v[6:7]
	v_mov_b64_e32 v[36:37], v[4:5]
	v_mov_b64_e32 v[34:35], v[2:3]
	v_mov_b64_e32 v[62:63], v[14:15]
	v_mov_b64_e32 v[60:61], v[12:13]
	v_mov_b64_e32 v[58:59], v[10:11]
	v_mov_b64_e32 v[56:57], v[8:9]
	v_mov_b64_e32 v[54:55], v[6:7]
	v_mov_b64_e32 v[52:53], v[4:5]
	v_mov_b64_e32 v[50:51], v[2:3]
	v_readfirstlane_b32 s6, v166
	s_cmp_lt_u32 s6, 0x100
	s_cbranch_scc1 .Lmla_prio_done
	s_setprio 1
.Lmla_prio_done:
	s_barrier
	s_branch .LBB0_867
.LBB0_866:
	v_sub_f32_e32 v74, v212, v198
	v_sub_f32_e32 v75, v211, v198
	v_sub_f32_e32 v76, v210, v198
	v_sub_f32_e32 v77, v208, v198
	v_sub_f32_e32 v78, v207, v198
	v_sub_f32_e32 v79, v206, v198
	v_sub_f32_e32 v80, v205, v198
	v_sub_f32_e32 v81, v204, v198
	v_sub_f32_e32 v73, v73, v198
	v_sub_f32_e32 v72, v72, v198
	v_sub_f32_e32 v71, v71, v198
	v_sub_f32_e32 v70, v70, v198
	v_sub_f32_e32 v69, v69, v198
	v_sub_f32_e32 v68, v68, v198
	v_sub_f32_e32 v67, v67, v198
	v_sub_f32_e32 v66, v66, v198
	v_exp_f32_e32 v74, v74
	v_exp_f32_e32 v75, v75
	v_exp_f32_e32 v76, v76
	v_exp_f32_e32 v77, v77
	v_exp_f32_e32 v78, v78
	v_exp_f32_e32 v79, v79
	v_exp_f32_e32 v80, v80
	v_exp_f32_e32 v81, v81
	v_exp_f32_e32 v73, v73
	v_exp_f32_e32 v72, v72
	v_exp_f32_e32 v71, v71
	v_exp_f32_e32 v70, v70
	v_exp_f32_e32 v69, v69
	v_exp_f32_e32 v68, v68
	v_exp_f32_e32 v204, v67
	v_exp_f32_e32 v205, v66
	v_add_f32_e32 v66, v201, v74
	v_add_f32_e32 v66, v75, v66
	v_add_f32_e32 v66, v76, v66
	v_add_f32_e32 v66, v77, v66
	v_add_f32_e32 v66, v78, v66
	v_add_f32_e32 v66, v79, v66
	v_add_f32_e32 v66, v80, v66
	v_add_f32_e32 v66, v81, v66
	v_add_f32_e32 v66, v73, v66
	v_add_f32_e32 v66, v72, v66
	v_add_f32_e32 v66, v71, v66
	v_add_f32_e32 v66, v70, v66
	v_add_f32_e32 v66, v69, v66
	v_add_f32_e32 v66, v68, v66
	v_add_f32_e32 v66, v204, v66
	v_add_f32_e32 v201, v205, v66
	v_cvt_pk_bf16_f32 v66, v73, v72
	v_cvt_pk_bf16_f32 v67, v71, v70
	v_cvt_pk_bf16_f32 v68, v69, v68
	v_cvt_pk_bf16_f32 v69, v204, v205
	v_cvt_pk_bf16_f32 v70, v74, v75
	v_cvt_pk_bf16_f32 v71, v76, v77
	v_cvt_pk_bf16_f32 v72, v78, v79
	v_cvt_pk_bf16_f32 v73, v80, v81
	ds_read_b128 v[74:77], v202 offset:36864
	ds_read_b128 v[78:81], v203 offset:36864
	ds_read_b128 v[204:207], v202 offset:32768
	ds_read_b128 v[208:211], v203 offset:32768
	s_nop 0
	v_mfma_f32_32x32x16_bf16 v[50:65], v[138:141], v[70:73], v[50:65]
	v_mfma_f32_32x32x16_bf16 v[34:49], v[130:133], v[70:73], v[34:49]
	s_waitcnt lgkmcnt(0)
	v_mfma_f32_32x32x16_bf16 v[18:33], v[208:211], v[70:73], v[18:33]
	v_mfma_f32_32x32x16_bf16 v[2:17], v[78:81], v[70:73], v[2:17]
	v_mfma_f32_32x32x16_bf16 v[50:65], v[142:145], v[66:69], v[50:65]
	v_mfma_f32_32x32x16_bf16 v[34:49], v[134:137], v[66:69], v[34:49]
	v_mfma_f32_32x32x16_bf16 v[18:33], v[204:207], v[66:69], v[18:33]
	v_mfma_f32_32x32x16_bf16 v[2:17], v[74:77], v[66:69], v[2:17]
	s_nop 0
	s_add_i32 s3, s2, 1
	s_cmp_lg_u32 s2, 2
	s_waitcnt vmcnt(5)
	s_cselect_b32 s2, s3, 0
	s_add_u32 s0, s0, 0x80
	s_addc_u32 s1, s1, 0
	v_lshl_add_u64 v[158:159], v[158:159], 0, v[154:155]
	v_lshl_add_u64 v[160:161], v[160:161], 0, v[152:153]
	s_cmpk_eq_i32 s0, 0x1f80
	v_lshl_add_u64 v[162:163], v[162:163], 0, v[0:1]
	s_barrier
	s_cbranch_scc1 .LBB0_871
; template <bool MLA>
; __device__ __forceinline__ float attn_scores(f32x16& sa, float c1, float slope2, int qpos, int q0w, int kpos0, int h5, bool maskit) {
;     ...
; #pragma unroll
;         for (int r = 0; r < 16; ++r) {
;             float v = sa[r] * c1;
;             if (maskit && (kpos0 + 8 * (r >> 2) + (r & 3) + 4 * h5 >= L)) v = -INFINITY;
;             sa[r] = v;
;             mx = fmaxf(mx, v);
;         }
;     } else {
;         const float dq = (float)(qpos - kpos0 - 4 * h5);
;         const int rel = q0w - kpos0;
;         if (rel > 31 || rel < -31) {
;             const float sgn = rel > 0 ? 1.0f : -1.0f;
;             const float A = -sgn * slope2 * dq;
;             const float ss = sgn * slope2;
; #pragma unroll
;             for (int r = 0; r < 16; ++r) {
; template <bool MLA>
; __device__ __forceinline__ void attn_item(unsigned char* smem, const Params& p, int b, int hh, int qt) {
;     ...
;     for (int kt = 0; kt < NKT; ++kt) {
;         const int k0 = kt * 64;
;         const unsigned char* Kc = S0 + stage * STGB;
;         const unsigned char* Vc = Kc + KBYTES;
;         if (kt + 2 < NKT) { const int st2 = stage >= 1 ? stage - 1 : 2; ATTN_DMA(st2); }
;         bf16x8 ka[4], kb[4], kc[4], vf[8];
; #pragma unroll
;         for (int i = 0; i < 4; ++i) ka[i] = KRD(0, i);
;         SB_();
; #pragma unroll
;         for (int hf = 0; hf < 2; ++hf) {
;             if (hf == 1 && kt == NKT - 1) break;
;             f32x16 sa;
; #pragma unroll
;             for (int r = 0; r < 16; ++r) sa[r] = 0.f;
;             if constexpr (MLA) {
;                 __builtin_amdgcn_s_setprio(1);
; #pragma unroll
;                 for (int i = 0; i < 4; ++i) {
;                     sa = __builtin_amdgcn_mfma_f32_32x32x16_bf16(ka[i], qf[i], sa, 0, 0, 0);
;                     kb[i] = KRD(hf, 4 + i);
;                 }
;                 SB_();
; #pragma unroll
;                 for (int i = 0; i < 4; ++i) {
;                     sa = __builtin_amdgcn_mfma_f32_32x32x16_bf16(kb[i], qf[4 + i], sa, 0, 0, 0);
;                     kc[i] = KRD(hf, 8 + i);
;                 }
;                 SB_();
; #pragma unroll
;                 for (int d = 0; d < 2; ++d) { vf[2 * d] = VRD(hf, d, 0); vf[2 * d + 1] = VRD(hf, d, 1); }
; #pragma unroll
;                 for (int i = 0; i < 4; ++i) sa = __builtin_amdgcn_mfma_f32_32x32x16_bf16(kc[i], qf[8 + i], sa, 0, 0, 0);
.LBB0_867:
	s_mul_i32 s3, s2, 0xa000
	s_add_i32 s6, s3, 0xffff6000
	s_cmp_gt_i32 s2, 0
	s_cselect_b32 s6, s6, 0x14000
	v_add_u32_e32 v70, s6, v199
	v_add_u32_e32 v71, 0x2000, v70
	v_readfirstlane_b32 s6, v70
	s_mov_b32 m0, s6
	v_readfirstlane_b32 s6, v71
	v_add_u32_e32 v71, 0x4000, v70
	global_load_lds_dwordx4 v[162:163], off
	s_mov_b32 m0, s6
	v_readfirstlane_b32 s6, v71
	v_add_u32_e32 v71, 0x6000, v70
	global_load_lds_dwordx4 v[160:161], off
	s_mov_b32 m0, s6
	v_readfirstlane_b32 s6, v71
	v_lshl_add_u64 v[68:69], v[156:157], 0, s[0:1]
	global_load_lds_dwordx4 v[158:159], off
	s_mov_b32 m0, s6
	v_lshl_add_u64 v[66:67], v[164:165], 0, s[0:1]
	global_load_lds_dwordx4 v[68:69], off
	v_add_u32_e32 v68, 0x8000, v70
	v_add_u32_e32 v70, s3, v200
	v_readfirstlane_b32 s6, v68
	s_mov_b32 m0, s6
	v_add_u32_e32 v203, v70, v192
	global_load_lds_dwordx4 v[66:67], off
	v_add_u32_e32 v205, v70, v196
	v_add_u32_e32 v204, v70, v193
	ds_read_b128 v[66:69], v203
	ds_read_b128 v[130:133], v204
	v_add_u32_e32 v206, v70, v197
	ds_read_b128 v[134:137], v205
	ds_read_b128 v[138:141], v206
	v_or_b32_e32 v202, s3, v194
	s_nop 0
	s_waitcnt lgkmcnt(0)
	v_mfma_f32_32x32x16_bf16 v[66:81], v[66:69], v[110:113], 0
	ds_read_b128 v[142:145], v203 offset:128
	v_mfma_f32_32x32x16_bf16 v[66:81], v[130:133], v[106:109], v[66:81]
	ds_read_b128 v[130:133], v204 offset:128
	v_mfma_f32_32x32x16_bf16 v[66:81], v[134:137], v[102:105], v[66:81]
	ds_read_b128 v[134:137], v205 offset:128
	v_mfma_f32_32x32x16_bf16 v[66:81], v[138:141], v[98:101], v[66:81]
	ds_read_b128 v[138:141], v206 offset:128
	ds_read_b128 v[208:211], v203 offset:256
	ds_read_b128 v[212:215], v204 offset:256
	ds_read_b128 v[222:225], v205 offset:256
	ds_read_b128 v[226:229], v206 offset:256
	s_waitcnt lgkmcnt(0)
	v_mfma_f32_32x32x16_bf16 v[66:81], v[142:145], v[94:97], v[66:81]
	v_add_u32_e32 v207, v202, v193
	v_mfma_f32_32x32x16_bf16 v[66:81], v[130:133], v[90:93], v[66:81]
	v_mfma_f32_32x32x16_bf16 v[66:81], v[134:137], v[86:89], v[66:81]
	v_mfma_f32_32x32x16_bf16 v[66:81], v[138:141], v[82:85], v[66:81]
	v_mfma_f32_32x32x16_bf16 v[66:81], v[208:211], v[118:121], v[66:81]
	v_add_u32_e32 v208, v202, v192
	ds_read_b128 v[138:141], v208 offset:24576
	ds_read_b128 v[130:133], v208 offset:28672
	ds_read_b128 v[142:145], v207 offset:24576
	ds_read_b128 v[134:137], v207 offset:28672
	v_mfma_f32_32x32x16_bf16 v[66:81], v[212:215], v[126:129], v[66:81]
	v_mfma_f32_32x32x16_bf16 v[66:81], v[222:225], v[114:117], v[66:81]
	v_mfma_f32_32x32x16_bf16 v[66:81], v[226:229], v[122:125], v[66:81]
	s_nop 0
	s_nop 10
	v_mul_f32_e32 v217, 0x3dd53b94, v66
	v_mul_f32_e32 v216, 0x3dd53b94, v67
	s_mov_b32 s3, 0xff800000
	v_mul_f32_e32 v215, 0x3dd53b94, v68
	v_mul_f32_e32 v214, 0x3dd53b94, v69
	v_mul_f32_e32 v210, 0x3dd53b94, v73
	v_mul_f32_e32 v73, 0x3dd53b94, v74
	v_max3_f32 v74, v217, s3, v216
	v_mul_f32_e32 v213, 0x3dd53b94, v70
	v_mul_f32_e32 v212, 0x3dd53b94, v71
	v_max3_f32 v74, v74, v215, v214
	v_mul_f32_e32 v211, 0x3dd53b94, v72
	v_max3_f32 v74, v74, v213, v212
	v_mul_f32_e32 v72, 0x3dd53b94, v75
	v_max3_f32 v74, v74, v211, v210
	v_mul_f32_e32 v71, 0x3dd53b94, v76
	v_mul_f32_e32 v70, 0x3dd53b94, v77
	v_max3_f32 v74, v74, v73, v72
	v_mul_f32_e32 v69, 0x3dd53b94, v78
	v_mul_f32_e32 v68, 0x3dd53b94, v79
	v_max3_f32 v74, v74, v71, v70
	v_mul_f32_e32 v67, 0x3dd53b94, v80
	v_mul_f32_e32 v66, 0x3dd53b94, v81
	v_max3_f32 v74, v74, v69, v68
	v_max3_f32 v74, v74, v67, v66
	ds_bpermute_b32 v75, v149, v74
	v_add_f32_e32 v209, 0x41000000, v198
	s_waitcnt lgkmcnt(0)
	v_max_f32_e32 v75, v75, v75
	v_max_f32_e32 v74, v74, v75
	v_cmp_le_f32_e32 vcc, v74, v209
	s_cmp_eq_u64 vcc, exec
	s_cbranch_scc1 .LBB0_869
	v_max_f32_e32 v74, v74, v74
	v_max_f32_e32 v75, v198, v198
	v_max_f32_e32 v75, v75, v74
	v_sub_f32_e32 v74, v198, v75
	v_exp_f32_e32 v74, v74
	v_add_f32_e32 v209, 0x41000000, v75
	v_mov_b32_e32 v198, v75
	v_mul_f32_e32 v201, v201, v74
	v_pk_mul_f32 v[64:65], v[64:65], v[74:75] op_sel_hi:[1,0]
	v_pk_mul_f32 v[62:63], v[62:63], v[74:75] op_sel_hi:[1,0]
	v_pk_mul_f32 v[60:61], v[60:61], v[74:75] op_sel_hi:[1,0]
	v_pk_mul_f32 v[58:59], v[58:59], v[74:75] op_sel_hi:[1,0]
	v_pk_mul_f32 v[56:57], v[56:57], v[74:75] op_sel_hi:[1,0]
	v_pk_mul_f32 v[54:55], v[54:55], v[74:75] op_sel_hi:[1,0]
	v_pk_mul_f32 v[52:53], v[52:53], v[74:75] op_sel_hi:[1,0]
	v_pk_mul_f32 v[50:51], v[50:51], v[74:75] op_sel_hi:[1,0]
	v_pk_mul_f32 v[48:49], v[48:49], v[74:75] op_sel_hi:[1,0]
	v_pk_mul_f32 v[46:47], v[46:47], v[74:75] op_sel_hi:[1,0]
	v_pk_mul_f32 v[44:45], v[44:45], v[74:75] op_sel_hi:[1,0]
	v_pk_mul_f32 v[42:43], v[42:43], v[74:75] op_sel_hi:[1,0]
	v_pk_mul_f32 v[40:41], v[40:41], v[74:75] op_sel_hi:[1,0]
	v_pk_mul_f32 v[38:39], v[38:39], v[74:75] op_sel_hi:[1,0]
	v_pk_mul_f32 v[36:37], v[36:37], v[74:75] op_sel_hi:[1,0]
	v_pk_mul_f32 v[34:35], v[34:35], v[74:75] op_sel_hi:[1,0]
	v_pk_mul_f32 v[32:33], v[32:33], v[74:75] op_sel_hi:[1,0]
	v_pk_mul_f32 v[30:31], v[30:31], v[74:75] op_sel_hi:[1,0]
	v_pk_mul_f32 v[28:29], v[28:29], v[74:75] op_sel_hi:[1,0]
	v_pk_mul_f32 v[26:27], v[26:27], v[74:75] op_sel_hi:[1,0]
	v_pk_mul_f32 v[24:25], v[24:25], v[74:75] op_sel_hi:[1,0]
	v_pk_mul_f32 v[22:23], v[22:23], v[74:75] op_sel_hi:[1,0]
	v_pk_mul_f32 v[20:21], v[20:21], v[74:75] op_sel_hi:[1,0]
	v_pk_mul_f32 v[18:19], v[18:19], v[74:75] op_sel_hi:[1,0]
	v_pk_mul_f32 v[16:17], v[16:17], v[74:75] op_sel_hi:[1,0]
	v_pk_mul_f32 v[14:15], v[14:15], v[74:75] op_sel_hi:[1,0]
	v_pk_mul_f32 v[12:13], v[12:13], v[74:75] op_sel_hi:[1,0]
	v_pk_mul_f32 v[10:11], v[10:11], v[74:75] op_sel_hi:[1,0]
	v_pk_mul_f32 v[8:9], v[8:9], v[74:75] op_sel_hi:[1,0]
	v_pk_mul_f32 v[6:7], v[6:7], v[74:75] op_sel_hi:[1,0]
	v_pk_mul_f32 v[4:5], v[4:5], v[74:75] op_sel_hi:[1,0]
	v_pk_mul_f32 v[2:3], v[2:3], v[74:75] op_sel_hi:[1,0]
; __device__ __forceinline__ void attn_exp(f32x16& sa, float mx, float& m_run, float& lsum, f32x16 (&o)[4], bf16x8& pb0, bf16x8& pb1) {
;     if (!__all(mx <= m_run + ATT_THR)) {
;         const float m_new = fmaxf(m_run, mx);
;         const float alpha = __builtin_amdgcn_exp2f(m_run - m_new);
;         m_run = m_new;
;         lsum *= alpha;
; #pragma unroll
;         for (int d = 0; d < 4; ++d)
; #pragma unroll
;             for (int r = 0; r < 16; ++r) o[d][r] *= alpha;
;     }
;     float pv[16];
; #pragma unroll
;     for (int r = 0; r < 16; ++r) { pv[r] = __builtin_amdgcn_exp2f(sa[r] - m_run); lsum += pv[r]; }
;     u32x4 t0 = {pack2(pv[0], pv[1]), pack2(pv[2], pv[3]), pack2(pv[4], pv[5]), pack2(pv[6], pv[7])};
;     u32x4 t1 = {pack2(pv[8], pv[9]), pack2(pv[10], pv[11]), pack2(pv[12], pv[13]), pack2(pv[14], pv[15])};
;     pb0 = __builtin_bit_cast(bf16x8, t0);
;     pb1 = __builtin_bit_cast(bf16x8, t1);
; template <bool MLA>
; __device__ __forceinline__ void attn_item(unsigned char* smem, const Params& p, int b, int hh, int qt) {
;     ...
;                 for (int i = 0; i < 4; ++i) {
;                     sa = __builtin_amdgcn_mfma_f32_32x32x16_bf16(ka[i], qf[i], sa, 0, 0, 0);
;                     kb[i] = KRD(hf, 4 + i);
;                 }
;                 SB_();
; #pragma unroll
;                 for (int i = 0; i < 4; ++i) {
;                     sa = __builtin_amdgcn_mfma_f32_32x32x16_bf16(kb[i], qf[4 + i], sa, 0, 0, 0);
;                     kc[i] = KRD(hf, 8 + i);
;                 }
;                 SB_();
; #pragma unroll
;                 for (int d = 0; d < 2; ++d) { vf[2 * d] = VRD(hf, d, 0); vf[2 * d + 1] = VRD(hf, d, 1); }
; #pragma unroll
;                 for (int i = 0; i < 4; ++i) sa = __builtin_amdgcn_mfma_f32_32x32x16_bf16(kc[i], qf[8 + i], sa, 0, 0, 0);
;                 __builtin_amdgcn_s_setprio(0);
;             } else {
; #pragma unroll
;                 for (int i = 0; i < 4; ++i) sa = __builtin_amdgcn_mfma_f32_32x32x16_bf16(ka[i], qf[i], sa, 0, 0, 0);
;                 SB_();
;                 const float mx = attn_scores<false>(sa, c1, slope2, qpos, q0w, k0 + hf * 32, h5, kt == NKT - 1);
;                 const bool skip = __all(mx < m_run - 40.0f);
;                 if (hf == 0 && kt != NKT - 1) {
; #pragma unroll
;                     for (int i = 0; i < 4; ++i) ka[i] = KRD(1, i);
;                 }
.LBB0_869:
	v_sub_f32_e32 v74, v217, v198
	v_exp_f32_e32 v222, v74
	v_sub_f32_e32 v74, v216, v198
	v_exp_f32_e32 v223, v74
	v_sub_f32_e32 v74, v215, v198
	v_exp_f32_e32 v224, v74
	v_sub_f32_e32 v74, v214, v198
	v_exp_f32_e32 v225, v74
	v_sub_f32_e32 v74, v213, v198
	v_exp_f32_e32 v226, v74
	v_sub_f32_e32 v74, v212, v198
	v_exp_f32_e32 v227, v74
	v_sub_f32_e32 v74, v211, v198
	v_exp_f32_e32 v228, v74
	v_sub_f32_e32 v74, v210, v198
	v_sub_f32_e32 v73, v73, v198
	v_sub_f32_e32 v72, v72, v198
	v_sub_f32_e32 v71, v71, v198
	v_sub_f32_e32 v70, v70, v198
	v_sub_f32_e32 v69, v69, v198
	v_sub_f32_e32 v68, v68, v198
	v_sub_f32_e32 v67, v67, v198
	v_sub_f32_e32 v66, v66, v198
	v_exp_f32_e32 v229, v74
	v_exp_f32_e32 v230, v73
	v_exp_f32_e32 v231, v72
	v_exp_f32_e32 v232, v71
	v_exp_f32_e32 v233, v70
	v_exp_f32_e32 v234, v69
	v_exp_f32_e32 v235, v68
	v_exp_f32_e32 v236, v67
	v_exp_f32_e32 v237, v66
	v_cvt_pk_bf16_f32 v66, v222, v223
	v_cvt_pk_bf16_f32 v67, v224, v225
	v_cvt_pk_bf16_f32 v68, v226, v227
	v_cvt_pk_bf16_f32 v69, v228, v229
	v_cvt_pk_bf16_f32 v70, v230, v231
	v_cvt_pk_bf16_f32 v71, v232, v233
	v_cvt_pk_bf16_f32 v72, v234, v235
	v_cvt_pk_bf16_f32 v73, v236, v237
	v_add_f32_e32 v201, v201, v222
	v_add_f32_e32 v201, v223, v201
	v_add_f32_e32 v201, v224, v201
	v_add_f32_e32 v201, v225, v201
	v_add_f32_e32 v201, v226, v201
	v_add_f32_e32 v201, v227, v201
	v_add_f32_e32 v201, v228, v201
	v_add_f32_e32 v201, v229, v201
	v_add_f32_e32 v201, v230, v201
	v_add_f32_e32 v201, v231, v201
	v_add_f32_e32 v201, v232, v201
	v_add_f32_e32 v201, v233, v201
	v_add_f32_e32 v201, v234, v201
	v_add_f32_e32 v201, v235, v201
	v_add_f32_e32 v201, v236, v201
	ds_read_b128 v[74:77], v208 offset:32768
	ds_read_b128 v[78:81], v207 offset:32768
	ds_read_b128 v[210:213], v208 offset:36864
	ds_read_b128 v[214:217], v207 offset:36864
	v_add_f32_e32 v201, v237, v201
	ds_read_b128 v[222:225], v203 offset:12288
	ds_read_b128 v[226:229], v204 offset:12288
	ds_read_b128 v[230:233], v205 offset:12288
	ds_read_b128 v[234:237], v206 offset:12288
	s_nop 0
	v_mfma_f32_32x32x16_bf16 v[50:65], v[138:141], v[66:69], v[50:65]
	v_mfma_f32_32x32x16_bf16 v[34:49], v[130:133], v[66:69], v[34:49]
	s_waitcnt lgkmcnt(0)
	v_mfma_f32_32x32x16_bf16 v[18:33], v[74:77], v[66:69], v[18:33]
	v_mfma_f32_32x32x16_bf16 v[2:17], v[210:213], v[66:69], v[2:17]
	v_mfma_f32_32x32x16_bf16 v[50:65], v[142:145], v[70:73], v[50:65]
	v_mfma_f32_32x32x16_bf16 v[34:49], v[134:137], v[70:73], v[34:49]
	v_mfma_f32_32x32x16_bf16 v[18:33], v[78:81], v[70:73], v[18:33]
	v_mfma_f32_32x32x16_bf16 v[2:17], v[214:217], v[70:73], v[2:17]
	s_nop 0
	s_nop 0
	v_mfma_f32_32x32x16_bf16 v[66:81], v[222:225], v[110:113], 0
	ds_read_b128 v[130:133], v203 offset:12416
	ds_read_b128 v[134:137], v204 offset:12416
	ds_read_b128 v[138:141], v205 offset:12416
	ds_read_b128 v[142:145], v206 offset:12416
	v_mfma_f32_32x32x16_bf16 v[66:81], v[226:229], v[106:109], v[66:81]
	v_mfma_f32_32x32x16_bf16 v[66:81], v[230:233], v[102:105], v[66:81]
	v_mfma_f32_32x32x16_bf16 v[66:81], v[234:237], v[98:101], v[66:81]
	ds_read_b128 v[210:213], v203 offset:12544
	ds_read_b128 v[214:217], v204 offset:12544
	ds_read_b128 v[222:225], v205 offset:12544
	ds_read_b128 v[204:207], v206 offset:12544
	s_waitcnt lgkmcnt(0)
	v_mfma_f32_32x32x16_bf16 v[66:81], v[130:133], v[94:97], v[66:81]
	v_add_u32_e32 v203, v202, v196
	v_add_u32_e32 v202, v202, v197
	v_mfma_f32_32x32x16_bf16 v[66:81], v[134:137], v[90:93], v[66:81]
	v_mfma_f32_32x32x16_bf16 v[66:81], v[138:141], v[86:89], v[66:81]
	v_mfma_f32_32x32x16_bf16 v[66:81], v[142:145], v[82:85], v[66:81]
	ds_read_b128 v[138:141], v203 offset:24576
	ds_read_b128 v[130:133], v203 offset:28672
	ds_read_b128 v[142:145], v202 offset:24576
	ds_read_b128 v[134:137], v202 offset:28672
	v_mfma_f32_32x32x16_bf16 v[66:81], v[210:213], v[118:121], v[66:81]
	v_mfma_f32_32x32x16_bf16 v[66:81], v[214:217], v[126:129], v[66:81]
	v_mfma_f32_32x32x16_bf16 v[66:81], v[222:225], v[114:117], v[66:81]
	v_mfma_f32_32x32x16_bf16 v[66:81], v[204:207], v[122:125], v[66:81]
	s_nop 0
	s_nop 10
	v_mul_f32_e32 v212, 0x3dd53b94, v66
	v_mul_f32_e32 v211, 0x3dd53b94, v67
	v_mul_f32_e32 v210, 0x3dd53b94, v68
	v_mul_f32_e32 v208, 0x3dd53b94, v69
	v_mul_f32_e32 v204, 0x3dd53b94, v73
	v_mul_f32_e32 v73, 0x3dd53b94, v74
	v_max3_f32 v74, v212, s3, v211
	v_mul_f32_e32 v207, 0x3dd53b94, v70
	v_mul_f32_e32 v206, 0x3dd53b94, v71
	v_max3_f32 v74, v74, v210, v208
	v_mul_f32_e32 v205, 0x3dd53b94, v72
	v_max3_f32 v74, v74, v207, v206
	v_mul_f32_e32 v72, 0x3dd53b94, v75
	v_max3_f32 v74, v74, v205, v204
	v_mul_f32_e32 v71, 0x3dd53b94, v76
	v_mul_f32_e32 v70, 0x3dd53b94, v77
	v_max3_f32 v74, v74, v73, v72
	v_mul_f32_e32 v69, 0x3dd53b94, v78
	v_mul_f32_e32 v68, 0x3dd53b94, v79
	v_max3_f32 v74, v74, v71, v70
	v_mul_f32_e32 v67, 0x3dd53b94, v80
	v_mul_f32_e32 v66, 0x3dd53b94, v81
	v_max3_f32 v74, v74, v69, v68
	v_max3_f32 v74, v74, v67, v66
	ds_bpermute_b32 v75, v149, v74
	s_waitcnt lgkmcnt(0)
	v_max_f32_e32 v75, v75, v75
	v_max_f32_e32 v74, v74, v75
	v_cmp_le_f32_e32 vcc, v74, v209
	s_cmp_eq_u64 vcc, exec
	s_cbranch_scc1 .LBB0_866
; __device__ __forceinline__ void attn_exp(f32x16& sa, float mx, float& m_run, float& lsum, f32x16 (&o)[4], bf16x8& pb0, bf16x8& pb1) {
;     if (!__all(mx <= m_run + ATT_THR)) {
;         const float m_new = fmaxf(m_run, mx);
;         const float alpha = __builtin_amdgcn_exp2f(m_run - m_new);
;         m_run = m_new;
;         lsum *= alpha;
; #pragma unroll
;         for (int d = 0; d < 4; ++d)
; #pragma unroll
;             for (int r = 0; r < 16; ++r) o[d][r] *= alpha;
;     }
	v_max_f32_e32 v74, v74, v74
	v_max_f32_e32 v75, v198, v198
	v_max_f32_e32 v75, v75, v74
	v_sub_f32_e32 v74, v198, v75
	v_exp_f32_e32 v74, v74
	v_mov_b32_e32 v198, v75
	v_mul_f32_e32 v201, v201, v74
	v_pk_mul_f32 v[64:65], v[64:65], v[74:75] op_sel_hi:[1,0]
	v_pk_mul_f32 v[62:63], v[62:63], v[74:75] op_sel_hi:[1,0]
	v_pk_mul_f32 v[60:61], v[60:61], v[74:75] op_sel_hi:[1,0]
	v_pk_mul_f32 v[58:59], v[58:59], v[74:75] op_sel_hi:[1,0]
	v_pk_mul_f32 v[56:57], v[56:57], v[74:75] op_sel_hi:[1,0]
	v_pk_mul_f32 v[54:55], v[54:55], v[74:75] op_sel_hi:[1,0]
	v_pk_mul_f32 v[52:53], v[52:53], v[74:75] op_sel_hi:[1,0]
	v_pk_mul_f32 v[50:51], v[50:51], v[74:75] op_sel_hi:[1,0]
	v_pk_mul_f32 v[48:49], v[48:49], v[74:75] op_sel_hi:[1,0]
	v_pk_mul_f32 v[46:47], v[46:47], v[74:75] op_sel_hi:[1,0]
	v_pk_mul_f32 v[44:45], v[44:45], v[74:75] op_sel_hi:[1,0]
	v_pk_mul_f32 v[42:43], v[42:43], v[74:75] op_sel_hi:[1,0]
	v_pk_mul_f32 v[40:41], v[40:41], v[74:75] op_sel_hi:[1,0]
	v_pk_mul_f32 v[38:39], v[38:39], v[74:75] op_sel_hi:[1,0]
	v_pk_mul_f32 v[36:37], v[36:37], v[74:75] op_sel_hi:[1,0]
	v_pk_mul_f32 v[34:35], v[34:35], v[74:75] op_sel_hi:[1,0]
	v_pk_mul_f32 v[32:33], v[32:33], v[74:75] op_sel_hi:[1,0]
	v_pk_mul_f32 v[30:31], v[30:31], v[74:75] op_sel_hi:[1,0]
	v_pk_mul_f32 v[28:29], v[28:29], v[74:75] op_sel_hi:[1,0]
	v_pk_mul_f32 v[26:27], v[26:27], v[74:75] op_sel_hi:[1,0]
	v_pk_mul_f32 v[24:25], v[24:25], v[74:75] op_sel_hi:[1,0]
	v_pk_mul_f32 v[22:23], v[22:23], v[74:75] op_sel_hi:[1,0]
	v_pk_mul_f32 v[20:21], v[20:21], v[74:75] op_sel_hi:[1,0]
	v_pk_mul_f32 v[18:19], v[18:19], v[74:75] op_sel_hi:[1,0]
	v_pk_mul_f32 v[16:17], v[16:17], v[74:75] op_sel_hi:[1,0]
	v_pk_mul_f32 v[14:15], v[14:15], v[74:75] op_sel_hi:[1,0]
	v_pk_mul_f32 v[12:13], v[12:13], v[74:75] op_sel_hi:[1,0]
	v_pk_mul_f32 v[10:11], v[10:11], v[74:75] op_sel_hi:[1,0]
	v_pk_mul_f32 v[8:9], v[8:9], v[74:75] op_sel_hi:[1,0]
	v_pk_mul_f32 v[6:7], v[6:7], v[74:75] op_sel_hi:[1,0]
	v_pk_mul_f32 v[4:5], v[4:5], v[74:75] op_sel_hi:[1,0]
	v_pk_mul_f32 v[2:3], v[2:3], v[74:75] op_sel_hi:[1,0]
	s_branch .LBB0_866
